# r1+r3lite K-loop, ret_out epilogue stores widened to dwordx4 via v_permlane16_swap (vmcnt recounted), next-task L2 prefetch in ret_out
# speedup vs baseline: 1.0088x; 1.0057x over previous
; __device__ __forceinline__ void ret_out(const bf16_t* proj, const float* cosT, const float* sinT, const float* decay, const float* gn_g, const float* gn_b,
;                         const bf16_t* states, bf16_t* mix, unsigned char* lds, int tid, int bx) {
;     ...
;         bf16x8 pf[4];
; #pragma unroll
;         for (int s = 0; s < 4; ++s) {
;             f32x4 st2[2];
; #pragma unroll
;             for (int pp = 0; pp < 2; ++pp) {
;                 const bf16_t* kr = Kl + (32 * s + 8 * (fr >> 2) + 4 * pp + (fr & 3)) * LP + 8 * fq;
;                 f32x4 a = (f32x4){0.f, 0.f, 0.f, 0.f};
; #pragma unroll
;                 for (int ks = 0; ks < 4; ++ks) a = __builtin_amdgcn_mfma_f32_16x16x32_bf16(*(const bf16x8*)(kr + 32 * ks), qf[ks], a, 0, 0, 0);
; #pragma unroll
;                 for (int r = 0; r < 4; ++r) { const int sk = 32 * s + 8 * fq + 4 * pp + r, diff = cq - sk;
;                     const float df = (float)diff;
;                     const float dd = __builtin_amdgcn_exp2f(fminf(lgf2 * df, -lgb2 * df)) + fmaxf(1.0f - fabsf(df), 0.0f);
;                     a[r] *= dd * 0.08838834764831845f; }
;                 st2[pp] = a;
;             }
;             const u32x4 pw = (u32x4){cvt_pk_bf16(st2[0][0], st2[0][1]), cvt_pk_bf16(st2[0][2], st2[0][3]), cvt_pk_bf16(st2[1][0], st2[1][1]), cvt_pk_bf16(st2[1][2], st2[1][3])};
;             __builtin_memcpy(&pf[s], &pw, 16);
.Lro_nopf:
	v_lshlrev_b32_e32 v142, 16, v69
	v_cvt_pk_bf16_f32 v11, v16, v17
	v_lshlrev_b32_e32 v16, 1, v22
	v_and_b32_e32 v17, 3, v22
	v_and_or_b32 v16, v16, 24, v17
	v_mul_u32_u24_e32 v16, 0x110, v16
	v_add3_u32 v52, 0, v62, v16
	ds_read_b128 v[16:19], v52
	ds_read_b128 v[20:23], v52 offset:64
	s_waitcnt lgkmcnt(1)
	v_mfma_f32_16x16x32_bf16 v[16:19], v[16:19], v[4:7], 0
	ds_read_b128 v[24:27], v52 offset:1152
	v_and_b32_e32 v143, 0xffff0000, v69
	v_lshlrev_b32_e32 v146, 16, v68
	s_waitcnt lgkmcnt(1)
	v_mfma_f32_16x16x32_bf16 v[16:19], v[20:23], v[12:15], v[16:19]
	ds_read_b128 v[20:23], v52 offset:128
	v_and_b32_e32 v147, 0xffff0000, v68
	s_waitcnt lgkmcnt(0)
	v_mfma_f32_16x16x32_bf16 v[16:19], v[20:23], v[0:3], v[16:19]
	ds_read_b128 v[20:23], v52 offset:192
	s_waitcnt lgkmcnt(0)
	v_mfma_f32_16x16x32_bf16 v[16:19], v[20:23], v[8:11], v[16:19]
	v_cvt_f32_i32_e32 v20, v53
	v_mul_f32_e32 v21, v87, v20
	v_mul_f32_e32 v22, v63, v20
	v_sub_f32_e64 v20, 1.0, |v20|
	v_max_f32_e32 v30, 0, v20
	v_xad_u32 v20, v154, -1, v86
	v_cvt_f32_i32_e32 v20, v20
	v_min_f32_e32 v21, v21, v22
	v_exp_f32_e32 v28, v21
	v_mul_f32_e32 v21, v87, v20
	v_mul_f32_e32 v22, v63, v20
	v_sub_f32_e64 v20, 1.0, |v20|
	v_max_f32_e32 v31, 0, v20
	v_add_u32_e32 v20, -2, v53
	v_cvt_f32_i32_e32 v20, v20
	v_min_f32_e32 v21, v21, v22
	v_exp_f32_e32 v29, v21
	v_mul_f32_e32 v21, v87, v20
	v_mul_f32_e32 v22, v63, v20
	v_sub_f32_e64 v20, 1.0, |v20|
	v_max_f32_e32 v34, 0, v20
	v_add_u32_e32 v20, -3, v53
	v_cvt_f32_i32_e32 v20, v20
	v_min_f32_e32 v21, v21, v22
	v_exp_f32_e32 v32, v21
	v_pk_add_f32 v[28:29], v[28:29], v[30:31]
	v_mul_f32_e32 v21, v87, v20
	v_mul_f32_e32 v22, v63, v20
	v_min_f32_e32 v21, v21, v22
	v_sub_f32_e64 v20, 1.0, |v20|
	v_exp_f32_e32 v33, v21
	v_max_f32_e32 v35, 0, v20
	ds_read_b128 v[20:23], v52 offset:1088
	s_waitcnt lgkmcnt(0)
	v_mfma_f32_16x16x32_bf16 v[20:23], v[20:23], v[4:7], 0
	v_mul_f32_e64 v28, v28, s54
	v_mul_f32_e64 v29, v29, s54
	v_pk_mul_f32 v[16:17], v[28:29], v[16:17]
	v_mfma_f32_16x16x32_bf16 v[20:23], v[24:27], v[12:15], v[20:23]
	ds_read_b128 v[24:27], v52 offset:1216
	v_pk_add_f32 v[28:29], v[32:33], v[34:35]
	v_cvt_pk_bf16_f32 v16, v16, v17
	s_waitcnt lgkmcnt(0)
	v_mfma_f32_16x16x32_bf16 v[20:23], v[24:27], v[0:3], v[20:23]
	ds_read_b128 v[24:27], v52 offset:1280
	v_pk_mul_f32 v[28:29], v[28:29], s[54:55] op_sel_hi:[1,0]
	s_waitcnt lgkmcnt(0)
	v_mfma_f32_16x16x32_bf16 v[20:23], v[24:27], v[8:11], v[20:23]
	v_add_u32_e32 v24, -4, v53
	v_cvt_f32_i32_e32 v25, v24
	v_pk_mul_f32 v[18:19], v[28:29], v[18:19]
	v_or_b32_e32 v28, 32, v154
	v_cvt_pk_bf16_f32 v17, v18, v19
	v_mul_f32_e32 v24, v87, v25
	v_mul_f32_e32 v26, v63, v25
	v_sub_f32_e64 v25, 1.0, |v25|
	v_min_f32_e32 v24, v24, v26
	v_max_f32_e32 v26, 0, v25
	v_add_u32_e32 v25, -5, v53
	v_cvt_f32_i32_e32 v27, v25
	v_exp_f32_e32 v24, v24
	v_mul_f32_e32 v25, v87, v27
	v_mul_f32_e32 v36, v63, v27
	v_min_f32_e32 v25, v25, v36
	v_add_u32_e32 v36, -6, v53
	v_cvt_f32_i32_e32 v37, v36
	v_exp_f32_e32 v25, v25
	v_sub_f32_e64 v27, 1.0, |v27|
	v_max_f32_e32 v27, 0, v27
	v_mul_f32_e32 v36, v87, v37
	v_mul_f32_e32 v38, v63, v37
	v_sub_f32_e64 v37, 1.0, |v37|
	v_min_f32_e32 v36, v36, v38
	v_max_f32_e32 v38, 0, v37
	v_add_u32_e32 v37, -7, v53
	v_cvt_f32_i32_e32 v39, v37
	v_exp_f32_e32 v36, v36
	v_pk_add_f32 v[18:19], v[24:25], v[26:27]
	ds_read_b128 v[24:27], v52 offset:8768
	v_mul_f32_e32 v37, v87, v39
	v_mul_f32_e32 v40, v63, v39
	v_min_f32_e32 v37, v37, v40
	v_exp_f32_e32 v37, v37
	v_sub_f32_e64 v39, 1.0, |v39|
	v_max_f32_e32 v39, 0, v39
	v_pk_mul_f32 v[18:19], v[18:19], s[54:55] op_sel_hi:[1,0]
	s_nop 0
	v_pk_mul_f32 v[18:19], v[18:19], v[20:21]
	v_pk_add_f32 v[20:21], v[36:37], v[38:39]
	v_cvt_pk_bf16_f32 v18, v18, v19
	v_pk_mul_f32 v[20:21], v[20:21], s[54:55] op_sel_hi:[1,0]
	s_nop 0
	v_pk_mul_f32 v[20:21], v[20:21], v[22:23]
	s_nop 0
	v_cvt_pk_bf16_f32 v19, v20, v21
	ds_read_b128 v[20:23], v52 offset:8704
	s_waitcnt lgkmcnt(0)
	v_mfma_f32_16x16x32_bf16 v[20:23], v[20:23], v[4:7], 0
	v_mfma_f32_16x16x32_bf16 v[20:23], v[24:27], v[12:15], v[20:23]
	ds_read_b128 v[24:27], v52 offset:8832
	s_waitcnt lgkmcnt(0)
	v_mfma_f32_16x16x32_bf16 v[20:23], v[24:27], v[0:3], v[20:23]
	ds_read_b128 v[24:27], v52 offset:8896
	s_waitcnt lgkmcnt(0)
	v_mfma_f32_16x16x32_bf16 v[20:23], v[24:27], v[8:11], v[20:23]
	v_sub_u32_e32 v24, v86, v28
	v_cvt_f32_i32_e32 v24, v24
	ds_read_b128 v[28:31], v52 offset:9856
	v_mul_f32_e32 v25, v87, v24
	v_mul_f32_e32 v26, v63, v24
	v_sub_f32_e64 v24, 1.0, |v24|
	v_max_f32_e32 v34, 0, v24
	v_subrev_u32_e32 v24, 33, v53
	v_cvt_f32_i32_e32 v24, v24
	v_min_f32_e32 v25, v25, v26
	v_exp_f32_e32 v32, v25
	v_mul_f32_e32 v25, v87, v24
	v_mul_f32_e32 v26, v63, v24
	v_sub_f32_e64 v24, 1.0, |v24|
	v_max_f32_e32 v35, 0, v24
	v_subrev_u32_e32 v24, 34, v53
	v_cvt_f32_i32_e32 v24, v24
	v_min_f32_e32 v25, v25, v26
	v_exp_f32_e32 v33, v25
	v_mul_f32_e32 v25, v87, v24
	v_mul_f32_e32 v26, v63, v24
	v_sub_f32_e64 v24, 1.0, |v24|
	v_max_f32_e32 v38, 0, v24
	v_subrev_u32_e32 v24, 35, v53
	v_cvt_f32_i32_e32 v24, v24
	v_min_f32_e32 v25, v25, v26
	v_exp_f32_e32 v36, v25
	v_pk_add_f32 v[32:33], v[32:33], v[34:35]
	v_mul_f32_e32 v25, v87, v24
	v_mul_f32_e32 v26, v63, v24
	v_min_f32_e32 v25, v25, v26
	v_sub_f32_e64 v24, 1.0, |v24|
	v_exp_f32_e32 v37, v25
	v_max_f32_e32 v39, 0, v24
	ds_read_b128 v[24:27], v52 offset:9792
	s_waitcnt lgkmcnt(0)
	v_mfma_f32_16x16x32_bf16 v[24:27], v[24:27], v[4:7], 0
	v_mul_f32_e64 v32, v32, s54
	v_mul_f32_e64 v33, v33, s54
	v_pk_mul_f32 v[20:21], v[32:33], v[20:21]
	v_mfma_f32_16x16x32_bf16 v[24:27], v[28:31], v[12:15], v[24:27]
	ds_read_b128 v[28:31], v52 offset:9920
	v_pk_add_f32 v[32:33], v[36:37], v[38:39]
	v_cvt_pk_bf16_f32 v20, v20, v21
	s_waitcnt lgkmcnt(0)
; __device__ __forceinline__ void ret_out(const bf16_t* proj, const float* cosT, const float* sinT, const float* decay, const float* gn_g, const float* gn_b,
;                         const bf16_t* states, bf16_t* mix, unsigned char* lds, int tid, int bx) {
;     ...
;         for (int s = 0; s < 4; ++s) {
;             f32x4 st2[2];
; #pragma unroll
;             for (int pp = 0; pp < 2; ++pp) {
;                 const bf16_t* kr = Kl + (32 * s + 8 * (fr >> 2) + 4 * pp + (fr & 3)) * LP + 8 * fq;
;                 f32x4 a = (f32x4){0.f, 0.f, 0.f, 0.f};
; #pragma unroll
;                 for (int ks = 0; ks < 4; ++ks) a = __builtin_amdgcn_mfma_f32_16x16x32_bf16(*(const bf16x8*)(kr + 32 * ks), qf[ks], a, 0, 0, 0);
; #pragma unroll
;                 for (int r = 0; r < 4; ++r) { const int sk = 32 * s + 8 * fq + 4 * pp + r, diff = cq - sk;
;                     const float df = (float)diff;
;                     const float dd = __builtin_amdgcn_exp2f(fminf(lgf2 * df, -lgb2 * df)) + fmaxf(1.0f - fabsf(df), 0.0f);
;                     a[r] *= dd * 0.08838834764831845f; }
;                 st2[pp] = a;
;             }
;             const u32x4 pw = (u32x4){cvt_pk_bf16(st2[0][0], st2[0][1]), cvt_pk_bf16(st2[0][2], st2[0][3]), cvt_pk_bf16(st2[1][0], st2[1][1]), cvt_pk_bf16(st2[1][2], st2[1][3])};
;             __builtin_memcpy(&pf[s], &pw, 16);
	v_mfma_f32_16x16x32_bf16 v[24:27], v[28:31], v[0:3], v[24:27]
	ds_read_b128 v[28:31], v52 offset:9984
	v_pk_mul_f32 v[32:33], v[32:33], s[54:55] op_sel_hi:[1,0]
	s_waitcnt lgkmcnt(0)
	v_mfma_f32_16x16x32_bf16 v[24:27], v[28:31], v[8:11], v[24:27]
	v_subrev_u32_e32 v28, 36, v53
	v_cvt_f32_i32_e32 v29, v28
	v_pk_mul_f32 v[22:23], v[32:33], v[22:23]
	v_or_b32_e32 v32, 64, v154
	v_cvt_pk_bf16_f32 v21, v22, v23
	v_mul_f32_e32 v28, v87, v29
	v_mul_f32_e32 v30, v63, v29
	v_sub_f32_e64 v29, 1.0, |v29|
	v_min_f32_e32 v28, v28, v30
	v_max_f32_e32 v30, 0, v29
	v_subrev_u32_e32 v29, 37, v53
	v_cvt_f32_i32_e32 v31, v29
	v_exp_f32_e32 v28, v28
	v_mul_f32_e32 v29, v87, v31
	v_mul_f32_e32 v40, v63, v31
	v_min_f32_e32 v29, v29, v40
	v_subrev_u32_e32 v40, 38, v53
	v_cvt_f32_i32_e32 v41, v40
	v_exp_f32_e32 v29, v29
	v_sub_f32_e64 v31, 1.0, |v31|
	v_max_f32_e32 v31, 0, v31
	v_mul_f32_e32 v40, v87, v41
	v_mul_f32_e32 v42, v63, v41
	v_sub_f32_e64 v41, 1.0, |v41|
	v_min_f32_e32 v40, v40, v42
	v_max_f32_e32 v42, 0, v41
	v_subrev_u32_e32 v41, 39, v53
	v_cvt_f32_i32_e32 v43, v41
	v_exp_f32_e32 v40, v40
	v_pk_add_f32 v[22:23], v[28:29], v[30:31]
	ds_read_b128 v[28:31], v52 offset:17472
	v_mul_f32_e32 v41, v87, v43
	v_mul_f32_e32 v44, v63, v43
	v_min_f32_e32 v41, v41, v44
	v_exp_f32_e32 v41, v41
	v_sub_f32_e64 v43, 1.0, |v43|
	v_max_f32_e32 v43, 0, v43
	v_pk_mul_f32 v[22:23], v[22:23], s[54:55] op_sel_hi:[1,0]
	s_nop 0
	v_pk_mul_f32 v[22:23], v[22:23], v[24:25]
	v_pk_add_f32 v[24:25], v[40:41], v[42:43]
	v_cvt_pk_bf16_f32 v22, v22, v23
	v_pk_mul_f32 v[24:25], v[24:25], s[54:55] op_sel_hi:[1,0]
	s_nop 0
	v_pk_mul_f32 v[24:25], v[24:25], v[26:27]
	s_nop 0
	v_cvt_pk_bf16_f32 v23, v24, v25
	ds_read_b128 v[24:27], v52 offset:17408
	s_waitcnt lgkmcnt(0)
	v_mfma_f32_16x16x32_bf16 v[24:27], v[24:27], v[4:7], 0
	v_mfma_f32_16x16x32_bf16 v[24:27], v[28:31], v[12:15], v[24:27]
	ds_read_b128 v[28:31], v52 offset:17536
	s_waitcnt lgkmcnt(0)
	v_mfma_f32_16x16x32_bf16 v[24:27], v[28:31], v[0:3], v[24:27]
	ds_read_b128 v[28:31], v52 offset:17600
	s_waitcnt lgkmcnt(0)
	v_mfma_f32_16x16x32_bf16 v[24:27], v[28:31], v[8:11], v[24:27]
	v_sub_u32_e32 v28, v86, v32
	v_cvt_f32_i32_e32 v28, v28
	ds_read_b128 v[32:35], v52 offset:18560
	v_mul_f32_e32 v29, v87, v28
	v_mul_f32_e32 v30, v63, v28
	v_sub_f32_e64 v28, 1.0, |v28|
	v_max_f32_e32 v38, 0, v28
	v_add_u32_e32 v28, 0xffffffbf, v53
	v_cvt_f32_i32_e32 v28, v28
	v_min_f32_e32 v29, v29, v30
	v_exp_f32_e32 v36, v29
	v_mul_f32_e32 v29, v87, v28
	v_mul_f32_e32 v30, v63, v28
	v_sub_f32_e64 v28, 1.0, |v28|
	v_max_f32_e32 v39, 0, v28
	v_add_u32_e32 v28, 0xffffffbe, v53
	v_cvt_f32_i32_e32 v28, v28
	v_min_f32_e32 v29, v29, v30
	v_exp_f32_e32 v37, v29
	v_mul_f32_e32 v29, v87, v28
	v_mul_f32_e32 v30, v63, v28
	v_sub_f32_e64 v28, 1.0, |v28|
	v_max_f32_e32 v42, 0, v28
	v_add_u32_e32 v28, 0xffffffbd, v53
	v_cvt_f32_i32_e32 v28, v28
	v_min_f32_e32 v29, v29, v30
	v_exp_f32_e32 v40, v29
	v_pk_add_f32 v[36:37], v[36:37], v[38:39]
	v_mul_f32_e32 v29, v87, v28
	v_mul_f32_e32 v30, v63, v28
	v_min_f32_e32 v29, v29, v30
	v_sub_f32_e64 v28, 1.0, |v28|
	v_exp_f32_e32 v41, v29
	v_max_f32_e32 v43, 0, v28
	ds_read_b128 v[28:31], v52 offset:18496
	s_waitcnt lgkmcnt(0)
	v_mfma_f32_16x16x32_bf16 v[28:31], v[28:31], v[4:7], 0
	v_mul_f32_e64 v36, v36, s54
	v_mul_f32_e64 v37, v37, s54
	v_pk_mul_f32 v[24:25], v[36:37], v[24:25]
	v_mfma_f32_16x16x32_bf16 v[28:31], v[32:35], v[12:15], v[28:31]
	ds_read_b128 v[32:35], v52 offset:18624
	s_waitcnt lgkmcnt(0)
	v_mfma_f32_16x16x32_bf16 v[28:31], v[32:35], v[0:3], v[28:31]
	ds_read_b128 v[32:35], v52 offset:18688
	s_waitcnt lgkmcnt(0)
	v_mfma_f32_16x16x32_bf16 v[28:31], v[32:35], v[8:11], v[28:31]
	v_add_u32_e32 v32, 0xffffffbc, v53
	v_cvt_f32_i32_e32 v33, v32
	v_mul_f32_e32 v32, v87, v33
	v_mul_f32_e32 v34, v63, v33
	v_sub_f32_e64 v33, 1.0, |v33|
	v_min_f32_e32 v32, v32, v34
	v_max_f32_e32 v34, 0, v33
	v_add_u32_e32 v33, 0xffffffbb, v53
	v_cvt_f32_i32_e32 v35, v33
	v_exp_f32_e32 v32, v32
	v_mul_f32_e32 v33, v87, v35
	v_mul_f32_e32 v44, v63, v35
	v_min_f32_e32 v33, v33, v44
	v_add_u32_e32 v44, 0xffffffba, v53
	v_cvt_f32_i32_e32 v45, v44
	v_exp_f32_e32 v33, v33
	v_sub_f32_e64 v35, 1.0, |v35|
	v_max_f32_e32 v35, 0, v35
	v_mul_f32_e32 v44, v87, v45
	v_mul_f32_e32 v46, v63, v45
	v_sub_f32_e64 v45, 1.0, |v45|
	v_min_f32_e32 v44, v44, v46
	v_max_f32_e32 v46, 0, v45
	v_add_u32_e32 v45, 0xffffffb9, v53
	v_cvt_f32_i32_e32 v47, v45
	v_exp_f32_e32 v44, v44
	v_mul_f32_e32 v45, v87, v47
	v_mul_f32_e32 v48, v63, v47
	v_min_f32_e32 v45, v45, v48
	v_cvt_pk_bf16_f32 v48, v24, v25
	v_pk_add_f32 v[24:25], v[40:41], v[42:43]
	v_exp_f32_e32 v45, v45
	v_pk_mul_f32 v[24:25], v[24:25], s[54:55] op_sel_hi:[1,0]
	v_sub_f32_e64 v47, 1.0, |v47|
	v_pk_mul_f32 v[24:25], v[24:25], v[26:27]
	v_max_f32_e32 v47, 0, v47
	v_cvt_pk_bf16_f32 v49, v24, v25
	v_pk_add_f32 v[24:25], v[32:33], v[34:35]
	v_or_b32_e32 v32, 0x60, v154
	v_pk_mul_f32 v[24:25], v[24:25], s[54:55] op_sel_hi:[1,0]
	s_nop 0
	v_pk_mul_f32 v[24:25], v[24:25], v[28:29]
	s_nop 0
	v_cvt_pk_bf16_f32 v50, v24, v25
	v_pk_add_f32 v[24:25], v[44:45], v[46:47]
	s_nop 0
	v_pk_mul_f32 v[24:25], v[24:25], s[54:55] op_sel_hi:[1,0]
	s_nop 0
	v_pk_mul_f32 v[24:25], v[24:25], v[30:31]
	ds_read_b128 v[28:31], v52 offset:26176
	v_cvt_pk_bf16_f32 v51, v24, v25
	ds_read_b128 v[24:27], v52 offset:26112
	s_waitcnt lgkmcnt(0)
	v_mfma_f32_16x16x32_bf16 v[24:27], v[24:27], v[4:7], 0
	v_mfma_f32_16x16x32_bf16 v[24:27], v[28:31], v[12:15], v[24:27]
	ds_read_b128 v[28:31], v52 offset:26240
	s_waitcnt lgkmcnt(0)
	v_mfma_f32_16x16x32_bf16 v[24:27], v[28:31], v[0:3], v[24:27]
	ds_read_b128 v[28:31], v52 offset:26304
	s_waitcnt lgkmcnt(0)
; __device__ __forceinline__ void ret_out(const bf16_t* proj, const float* cosT, const float* sinT, const float* decay, const float* gn_g, const float* gn_b,
;                         const bf16_t* states, bf16_t* mix, unsigned char* lds, int tid, int bx) {
;     ...
;         for (int s = 0; s < 4; ++s) {
;             f32x4 st2[2];
; #pragma unroll
;             for (int pp = 0; pp < 2; ++pp) {
;                 const bf16_t* kr = Kl + (32 * s + 8 * (fr >> 2) + 4 * pp + (fr & 3)) * LP + 8 * fq;
;                 f32x4 a = (f32x4){0.f, 0.f, 0.f, 0.f};
; #pragma unroll
;                 for (int ks = 0; ks < 4; ++ks) a = __builtin_amdgcn_mfma_f32_16x16x32_bf16(*(const bf16x8*)(kr + 32 * ks), qf[ks], a, 0, 0, 0);
; #pragma unroll
;                 for (int r = 0; r < 4; ++r) { const int sk = 32 * s + 8 * fq + 4 * pp + r, diff = cq - sk;
;                     const float df = (float)diff;
;                     const float dd = __builtin_amdgcn_exp2f(fminf(lgf2 * df, -lgb2 * df)) + fmaxf(1.0f - fabsf(df), 0.0f);
;                     a[r] *= dd * 0.08838834764831845f; }
;                 st2[pp] = a;
;             }
;             const u32x4 pw = (u32x4){cvt_pk_bf16(st2[0][0], st2[0][1]), cvt_pk_bf16(st2[0][2], st2[0][3]), cvt_pk_bf16(st2[1][0], st2[1][1]), cvt_pk_bf16(st2[1][2], st2[1][3])};
;             __builtin_memcpy(&pf[s], &pw, 16);
;         }
;         f32x4 acc[8];
; #pragma unroll
;         for (int e8 = 0; e8 < 8; ++e8) acc[e8] = (f32x4){0.f, 0.f, 0.f, 0.f};
; #pragma unroll
;         for (int s = 0; s < 4; ++s)
; #pragma unroll
;             for (int e8 = 0; e8 < 8; ++e8) acc[e8] = __builtin_amdgcn_mfma_f32_16x16x32_bf16(*(const bf16x8*)(Vl + (16 * e8 + fr) * LP + ((32 * s + 8 * fq) ^ ((e8 & 3) << 4))), pf[s], acc[e8], 0, 0, 0);
	v_mfma_f32_16x16x32_bf16 v[24:27], v[28:31], v[8:11], v[24:27]
	v_sub_u32_e32 v28, v86, v32
	v_cvt_f32_i32_e32 v28, v28
	ds_read_b128 v[32:35], v52 offset:27264
	v_mul_f32_e32 v29, v87, v28
	v_mul_f32_e32 v30, v63, v28
	v_sub_f32_e64 v28, 1.0, |v28|
	v_max_f32_e32 v38, 0, v28
	v_add_u32_e32 v28, 0xffffff9f, v53
	v_cvt_f32_i32_e32 v28, v28
	v_min_f32_e32 v29, v29, v30
	v_exp_f32_e32 v36, v29
	v_mul_f32_e32 v29, v87, v28
	v_mul_f32_e32 v30, v63, v28
	v_sub_f32_e64 v28, 1.0, |v28|
	v_max_f32_e32 v39, 0, v28
	v_add_u32_e32 v28, 0xffffff9e, v53
	v_cvt_f32_i32_e32 v28, v28
	v_min_f32_e32 v29, v29, v30
	v_exp_f32_e32 v37, v29
	v_mul_f32_e32 v29, v87, v28
	v_mul_f32_e32 v30, v63, v28
	v_sub_f32_e64 v28, 1.0, |v28|
	v_max_f32_e32 v42, 0, v28
	v_add_u32_e32 v28, 0xffffff9d, v53
	v_cvt_f32_i32_e32 v28, v28
	v_min_f32_e32 v29, v29, v30
	v_exp_f32_e32 v40, v29
	v_pk_add_f32 v[36:37], v[36:37], v[38:39]
	v_mul_f32_e32 v29, v87, v28
	v_mul_f32_e32 v30, v63, v28
	v_min_f32_e32 v29, v29, v30
	v_sub_f32_e64 v28, 1.0, |v28|
	v_exp_f32_e32 v41, v29
	v_max_f32_e32 v43, 0, v28
	ds_read_b128 v[28:31], v52 offset:27200
	s_waitcnt lgkmcnt(0)
	v_mfma_f32_16x16x32_bf16 v[28:31], v[28:31], v[4:7], 0
	v_mul_f32_e64 v36, v36, s54
	v_mul_f32_e64 v37, v37, s54
	v_pk_mul_f32 v[24:25], v[36:37], v[24:25]
	v_mfma_f32_16x16x32_bf16 v[28:31], v[32:35], v[12:15], v[28:31]
	ds_read_b128 v[32:35], v52 offset:27328
	v_pk_add_f32 v[36:37], v[40:41], v[42:43]
	v_cvt_pk_bf16_f32 v24, v24, v25
	s_waitcnt lgkmcnt(0)
	v_mfma_f32_16x16x32_bf16 v[28:31], v[32:35], v[0:3], v[28:31]
	ds_read_b128 v[32:35], v52 offset:27392
	v_pk_mul_f32 v[36:37], v[36:37], s[54:55] op_sel_hi:[1,0]
	s_waitcnt lgkmcnt(0)
	v_mfma_f32_16x16x32_bf16 v[28:31], v[32:35], v[8:11], v[28:31]
	v_add_u32_e32 v32, 0xffffff9c, v53
	v_cvt_f32_i32_e32 v33, v32
	v_pk_mul_f32 v[26:27], v[36:37], v[26:27]
	v_mul_f32_e32 v32, v87, v33
	v_mul_f32_e32 v34, v63, v33
	v_sub_f32_e64 v33, 1.0, |v33|
	v_min_f32_e32 v32, v32, v34
	v_max_f32_e32 v34, 0, v33
	v_add_u32_e32 v33, 0xffffff9b, v53
	v_cvt_f32_i32_e32 v35, v33
	v_exp_f32_e32 v32, v32
	v_cvt_pk_bf16_f32 v25, v26, v27
	v_mul_f32_e32 v33, v87, v35
	v_mul_f32_e32 v44, v63, v35
	v_min_f32_e32 v33, v33, v44
	v_add_u32_e32 v44, 0xffffff9a, v53
	v_cvt_f32_i32_e32 v45, v44
	v_exp_f32_e32 v33, v33
	v_sub_f32_e64 v35, 1.0, |v35|
	v_max_f32_e32 v35, 0, v35
	v_mul_f32_e32 v44, v87, v45
	v_mul_f32_e32 v46, v63, v45
	v_sub_f32_e64 v45, 1.0, |v45|
	v_min_f32_e32 v44, v44, v46
	v_max_f32_e32 v46, 0, v45
	v_add_u32_e32 v45, 0xffffff99, v53
	v_cvt_f32_i32_e32 v47, v45
	v_exp_f32_e32 v44, v44
	v_pk_add_f32 v[26:27], v[32:33], v[34:35]
	v_bitop3_b32 v53, v154, s0, v180 bitop3:0xc8
	v_mul_f32_e32 v45, v87, v47
	v_mul_f32_e32 v52, v63, v47
	v_min_f32_e32 v45, v45, v52
	v_exp_f32_e32 v45, v45
	v_sub_f32_e64 v47, 1.0, |v47|
	v_max_f32_e32 v47, 0, v47
	v_pk_mul_f32 v[26:27], v[26:27], s[54:55] op_sel_hi:[1,0]
	v_mad_u32_u24 v52, v83, s52, 0
	v_pk_mul_f32 v[26:27], v[26:27], v[28:29]
	v_pk_add_f32 v[28:29], v[44:45], v[46:47]
	v_add_u32_e32 v89, v52, v62
	v_pk_mul_f32 v[28:29], v[28:29], s[54:55] op_sel_hi:[1,0]
	v_xad_u32 v88, v62, 32, v52
	v_pk_mul_f32 v[28:29], v[28:29], v[30:31]
	v_cvt_pk_bf16_f32 v26, v26, v27
	v_cvt_pk_bf16_f32 v27, v28, v29
	ds_read_b128 v[28:31], v89 offset:34816
	ds_read_b128 v[36:39], v89 offset:43584
	ds_read_b128 v[32:35], v88 offset:39168
	ds_read_b128 v[40:43], v88 offset:47936
	ds_read_b128 v[44:47], v89 offset:52224
	ds_read_b128 v[90:93], v89 offset:60992
	ds_read_b128 v[54:57], v88 offset:56576
	ds_read_b128 v[94:97], v88 offset:65344
	s_waitcnt lgkmcnt(7)
	v_mfma_f32_16x16x32_bf16 v[28:31], v[28:31], v[16:19], 0
	s_lshl_b32 s0, s36, 9
	s_add_i32 s0, s0, 0
	s_cmpk_lt_i32 s49, 0x600
	s_waitcnt lgkmcnt(5)
	v_mfma_f32_16x16x32_bf16 v[32:35], v[32:35], v[16:19], 0
	v_mfma_f32_16x16x32_bf16 v[36:39], v[36:39], v[16:19], 0
	s_waitcnt lgkmcnt(4)
	v_mfma_f32_16x16x32_bf16 v[40:43], v[40:43], v[16:19], 0
	s_waitcnt lgkmcnt(3)
	v_mfma_f32_16x16x32_bf16 v[44:47], v[44:47], v[16:19], 0
	s_waitcnt lgkmcnt(1)
	v_mfma_f32_16x16x32_bf16 v[54:57], v[54:57], v[16:19], 0
	v_mfma_f32_16x16x32_bf16 v[90:93], v[90:93], v[16:19], 0
	s_waitcnt lgkmcnt(0)
	v_mfma_f32_16x16x32_bf16 v[16:19], v[94:97], v[16:19], 0
	ds_read_b128 v[94:97], v89 offset:34880
	s_waitcnt lgkmcnt(0)
	v_mfma_f32_16x16x32_bf16 v[28:31], v[94:97], v[20:23], v[28:31]
	ds_read_b128 v[94:97], v88 offset:39232
	s_waitcnt lgkmcnt(0)
	v_mfma_f32_16x16x32_bf16 v[32:35], v[94:97], v[20:23], v[32:35]
	ds_read_b128 v[94:97], v89 offset:43520
	s_waitcnt lgkmcnt(0)
	v_mfma_f32_16x16x32_bf16 v[36:39], v[94:97], v[20:23], v[36:39]
	ds_read_b128 v[94:97], v88 offset:47872
	s_waitcnt lgkmcnt(0)
	v_mfma_f32_16x16x32_bf16 v[40:43], v[94:97], v[20:23], v[40:43]
	ds_read_b128 v[94:97], v89 offset:52288
	s_waitcnt lgkmcnt(0)
	v_mfma_f32_16x16x32_bf16 v[44:47], v[94:97], v[20:23], v[44:47]
	ds_read_b128 v[94:97], v88 offset:56640
	s_waitcnt lgkmcnt(0)
	v_mfma_f32_16x16x32_bf16 v[54:57], v[94:97], v[20:23], v[54:57]
	ds_read_b128 v[94:97], v89 offset:60928
	s_waitcnt lgkmcnt(0)
	v_mfma_f32_16x16x32_bf16 v[90:93], v[94:97], v[20:23], v[90:93]
	ds_read_b128 v[94:97], v88 offset:65280
	s_waitcnt lgkmcnt(0)
	v_mfma_f32_16x16x32_bf16 v[16:19], v[94:97], v[20:23], v[16:19]
	ds_read_b128 v[20:23], v89 offset:34944
	s_waitcnt lgkmcnt(0)
	v_mfma_f32_16x16x32_bf16 v[20:23], v[20:23], v[48:51], v[28:31]
	s_nop 2
	ds_read_b128 v[28:31], v88 offset:39296
	s_waitcnt lgkmcnt(0)
	v_mfma_f32_16x16x32_bf16 v[94:97], v[28:31], v[48:51], v[32:35]
	ds_read_b128 v[28:31], v89 offset:43712
	s_nop 1
	ds_read_b128 v[32:35], v88 offset:48064
	s_waitcnt lgkmcnt(1)
; __device__ __forceinline__ void ret_out(const bf16_t* proj, const float* cosT, const float* sinT, const float* decay, const float* gn_g, const float* gn_b,
;                         const bf16_t* states, bf16_t* mix, unsigned char* lds, int tid, int bx) {
;     ...
;             for (int e8 = 0; e8 < 8; ++e8) acc[e8] = __builtin_amdgcn_mfma_f32_16x16x32_bf16(*(const bf16x8*)(Vl + (16 * e8 + fr) * LP + ((32 * s + 8 * fq) ^ ((e8 & 3) << 4))), pf[s], acc[e8], 0, 0, 0);
; #pragma unroll
;         for (int dir = 0; dir < 2; ++dir) {
;             const unsigned char* sl = lds + ST_OFF + dir * 32768 + fr * 256;
;             const float sc = dir == 0 ? __builtin_amdgcn_exp2f(lgf2 * (float)(cq + 1)) : __builtin_amdgcn_exp2f(lgb2 * (float)(128 - cq));
; #pragma unroll
;             for (int e8 = 0; e8 < 8; ++e8) {
;                 f32x4 a2 = (f32x4){0.f, 0.f, 0.f, 0.f};
; #pragma unroll
;                 for (int ks = 0; ks < 4; ++ks) a2 = __builtin_amdgcn_mfma_f32_16x16x32_bf16(*(const bf16x8*)(sl + e8 * 4096 + (((4 * ks + fq) ^ fr) << 4)), qf[ks], a2, 0, 0, 0);
;                 acc[e8] += a2 * sc;
;             }
	v_mfma_f32_16x16x32_bf16 v[28:31], v[28:31], v[48:51], v[36:39]
	s_nop 2
	ds_read_b128 v[36:39], v89 offset:52352
	s_waitcnt lgkmcnt(1)
	v_mfma_f32_16x16x32_bf16 v[32:35], v[32:35], v[48:51], v[40:43]
	s_nop 2
	ds_read_b128 v[40:43], v88 offset:56704
	s_waitcnt lgkmcnt(1)
	v_mfma_f32_16x16x32_bf16 v[36:39], v[36:39], v[48:51], v[44:47]
	s_nop 2
	ds_read_b128 v[44:47], v89 offset:61120
	s_waitcnt lgkmcnt(1)
	v_mfma_f32_16x16x32_bf16 v[40:43], v[40:43], v[48:51], v[54:57]
	s_nop 2
	ds_read_b128 v[54:57], v88 offset:65472
	s_waitcnt lgkmcnt(1)
	v_mfma_f32_16x16x32_bf16 v[44:47], v[44:47], v[48:51], v[90:93]
	s_nop 2
	v_lshl_add_u32 v90, v53, 1, v52
	s_waitcnt lgkmcnt(0)
	v_mfma_f32_16x16x32_bf16 v[48:51], v[54:57], v[48:51], v[16:19]
	ds_read_b128 v[52:55], v90 offset:43520
	s_nop 1
	ds_read_b128 v[16:19], v89 offset:35008
	s_waitcnt lgkmcnt(0)
	v_mfma_f32_16x16x32_bf16 v[20:23], v[16:19], v[24:27], v[20:23]
	ds_read_b128 v[16:19], v88 offset:39360
	v_mfma_f32_16x16x32_bf16 v[56:59], v[52:55], v[24:27], v[28:31]
	s_nop 2
	ds_read_b128 v[28:31], v88 offset:48000
	s_waitcnt lgkmcnt(0)
	v_mfma_f32_16x16x32_bf16 v[52:55], v[28:31], v[24:27], v[32:35]
	ds_read_b128 v[28:31], v89 offset:52416
	s_waitcnt lgkmcnt(0)
	v_mfma_f32_16x16x32_bf16 v[36:39], v[28:31], v[24:27], v[36:39]
	ds_read_b128 v[28:31], v88 offset:56768
	s_waitcnt lgkmcnt(0)
	v_mfma_f32_16x16x32_bf16 v[32:35], v[28:31], v[24:27], v[40:43]
	ds_read_b128 v[28:31], v90 offset:60928
	s_nop 1
	ds_read_b128 v[40:43], v88 offset:65408
	v_mfma_f32_16x16x32_bf16 v[16:19], v[16:19], v[24:27], v[94:97]
	s_waitcnt lgkmcnt(1)
	v_mfma_f32_16x16x32_bf16 v[28:31], v[28:31], v[24:27], v[44:47]
	s_waitcnt lgkmcnt(0)
	v_mfma_f32_16x16x32_bf16 v[24:27], v[40:43], v[24:27], v[48:51]
	v_lshl_add_u32 v41, v83, 8, s55
	v_sub_u32_e32 v40, 0x80, v86
	v_bitop3_b32 v43, v85, v83, 3 bitop3:0x6c
	v_cvt_f32_i32_e32 v40, v40
	v_lshl_add_u32 v43, v43, 4, v41
	ds_read_b128 v[44:47], v43
	v_bitop3_b32 v48, v84, v83, 4 bitop3:0x36
	v_mul_f32_e64 v40, -v63, v40
	v_lshl_add_u32 v63, v48, 4, v41
	ds_read_b128 v[48:51], v63
	s_waitcnt lgkmcnt(1)
	v_mfma_f32_16x16x32_bf16 v[44:47], v[44:47], v[4:7], 0
	v_exp_f32_e32 v42, v40
	v_add_u32_e32 v40, 1, v86
	v_cvt_f32_i32_e32 v40, v40
	s_waitcnt lgkmcnt(0)
	v_mfma_f32_16x16x32_bf16 v[44:47], v[48:51], v[12:15], v[44:47]
	v_bitop3_b32 v48, v84, v83, 8 bitop3:0x36
	v_lshl_add_u32 v100, v48, 4, v41
	ds_read_b128 v[48:51], v100
	s_waitcnt lgkmcnt(0)
	v_mfma_f32_16x16x32_bf16 v[44:47], v[48:51], v[0:3], v[44:47]
	v_bitop3_b32 v48, v84, v83, 12 bitop3:0x36
	v_lshl_add_u32 v83, v48, 4, v41
	ds_read_b128 v[48:51], v83
	v_mul_f32_e32 v40, v87, v40
	v_exp_f32_e32 v40, v40
	s_waitcnt lgkmcnt(0)
	v_mfma_f32_16x16x32_bf16 v[44:47], v[48:51], v[8:11], v[44:47]
	s_nop 7
	v_pk_fma_f32 v[48:49], v[40:41], v[46:47], v[22:23] op_sel_hi:[0,1,1]
	v_pk_fma_f32 v[50:51], v[40:41], v[44:45], v[20:21] op_sel_hi:[0,1,1]
	ds_read_b128 v[20:23], v43 offset:4096
	ds_read_b128 v[44:47], v63 offset:4096
	s_waitcnt lgkmcnt(1)
	v_mfma_f32_16x16x32_bf16 v[20:23], v[20:23], v[4:7], 0
	s_waitcnt lgkmcnt(0)
	v_mfma_f32_16x16x32_bf16 v[20:23], v[44:47], v[12:15], v[20:23]
	ds_read_b128 v[44:47], v100 offset:4096
	s_waitcnt lgkmcnt(0)
	v_mfma_f32_16x16x32_bf16 v[20:23], v[44:47], v[0:3], v[20:23]
	ds_read_b128 v[44:47], v83 offset:4096
	s_waitcnt lgkmcnt(0)
	v_mfma_f32_16x16x32_bf16 v[20:23], v[44:47], v[8:11], v[20:23]
	s_nop 7
	v_pk_fma_f32 v[44:45], v[40:41], v[22:23], v[18:19] op_sel_hi:[0,1,1]
	v_pk_fma_f32 v[46:47], v[40:41], v[20:21], v[16:17] op_sel_hi:[0,1,1]
	ds_read_b128 v[16:19], v43 offset:8192
	ds_read_b128 v[20:23], v63 offset:8192
	s_waitcnt lgkmcnt(1)
	v_mfma_f32_16x16x32_bf16 v[16:19], v[16:19], v[4:7], 0
	s_waitcnt lgkmcnt(0)
	v_mfma_f32_16x16x32_bf16 v[16:19], v[20:23], v[12:15], v[16:19]
	ds_read_b128 v[20:23], v100 offset:8192
	s_waitcnt lgkmcnt(0)
	v_mfma_f32_16x16x32_bf16 v[16:19], v[20:23], v[0:3], v[16:19]
	ds_read_b128 v[20:23], v83 offset:8192
	s_waitcnt lgkmcnt(0)
	v_mfma_f32_16x16x32_bf16 v[16:19], v[20:23], v[8:11], v[16:19]
	ds_read_b128 v[20:23], v63 offset:12288
	s_nop 6
	v_pk_fma_f32 v[58:59], v[40:41], v[18:19], v[58:59] op_sel_hi:[0,1,1]
	v_pk_fma_f32 v[56:57], v[40:41], v[16:17], v[56:57] op_sel_hi:[0,1,1]
	ds_read_b128 v[16:19], v43 offset:12288
	s_waitcnt lgkmcnt(0)
	v_mfma_f32_16x16x32_bf16 v[16:19], v[16:19], v[4:7], 0
	v_mfma_f32_16x16x32_bf16 v[16:19], v[20:23], v[12:15], v[16:19]
	ds_read_b128 v[20:23], v100 offset:12288
	s_waitcnt lgkmcnt(0)
	v_mfma_f32_16x16x32_bf16 v[16:19], v[20:23], v[0:3], v[16:19]
	ds_read_b128 v[20:23], v83 offset:12288
	s_waitcnt lgkmcnt(0)
	v_mfma_f32_16x16x32_bf16 v[16:19], v[20:23], v[8:11], v[16:19]
	ds_read_b128 v[20:23], v63 offset:16384
	s_nop 6
	v_pk_fma_f32 v[54:55], v[40:41], v[18:19], v[54:55] op_sel_hi:[0,1,1]
	v_pk_fma_f32 v[52:53], v[40:41], v[16:17], v[52:53] op_sel_hi:[0,1,1]
	ds_read_b128 v[16:19], v43 offset:16384
	s_waitcnt lgkmcnt(0)
	v_mfma_f32_16x16x32_bf16 v[16:19], v[16:19], v[4:7], 0
	v_mfma_f32_16x16x32_bf16 v[16:19], v[20:23], v[12:15], v[16:19]
	ds_read_b128 v[20:23], v100 offset:16384
	s_waitcnt lgkmcnt(0)
	v_mfma_f32_16x16x32_bf16 v[16:19], v[20:23], v[0:3], v[16:19]
	ds_read_b128 v[20:23], v83 offset:16384
	s_waitcnt lgkmcnt(0)
	v_mfma_f32_16x16x32_bf16 v[16:19], v[20:23], v[8:11], v[16:19]
	ds_read_b128 v[20:23], v63 offset:20480
	s_nop 6
	v_pk_fma_f32 v[84:85], v[40:41], v[18:19], v[38:39] op_sel_hi:[0,1,1]
	v_pk_fma_f32 v[86:87], v[40:41], v[16:17], v[36:37] op_sel_hi:[0,1,1]
	ds_read_b128 v[16:19], v43 offset:20480
	s_waitcnt lgkmcnt(0)
; __device__ __forceinline__ void ret_out(const bf16_t* proj, const float* cosT, const float* sinT, const float* decay, const float* gn_g, const float* gn_b,
;                         const bf16_t* states, bf16_t* mix, unsigned char* lds, int tid, int bx) {
;     ...
;         for (int dir = 0; dir < 2; ++dir) {
;             const unsigned char* sl = lds + ST_OFF + dir * 32768 + fr * 256;
;             const float sc = dir == 0 ? __builtin_amdgcn_exp2f(lgf2 * (float)(cq + 1)) : __builtin_amdgcn_exp2f(lgb2 * (float)(128 - cq));
; #pragma unroll
;             for (int e8 = 0; e8 < 8; ++e8) {
;                 f32x4 a2 = (f32x4){0.f, 0.f, 0.f, 0.f};
; #pragma unroll
;                 for (int ks = 0; ks < 4; ++ks) a2 = __builtin_amdgcn_mfma_f32_16x16x32_bf16(*(const bf16x8*)(sl + e8 * 4096 + (((4 * ks + fq) ^ fr) << 4)), qf[ks], a2, 0, 0, 0);
;                 acc[e8] += a2 * sc;
;             }
	v_mfma_f32_16x16x32_bf16 v[16:19], v[16:19], v[4:7], 0
	v_mfma_f32_16x16x32_bf16 v[16:19], v[20:23], v[12:15], v[16:19]
	ds_read_b128 v[20:23], v100 offset:20480
	s_waitcnt lgkmcnt(0)
	v_mfma_f32_16x16x32_bf16 v[16:19], v[20:23], v[0:3], v[16:19]
	ds_read_b128 v[20:23], v83 offset:20480
	s_waitcnt lgkmcnt(0)
	v_mfma_f32_16x16x32_bf16 v[16:19], v[20:23], v[8:11], v[16:19]
	ds_read_b128 v[20:23], v63 offset:24576
	s_nop 6
	v_pk_fma_f32 v[88:89], v[40:41], v[18:19], v[34:35] op_sel_hi:[0,1,1]
	v_pk_fma_f32 v[90:91], v[40:41], v[16:17], v[32:33] op_sel_hi:[0,1,1]
	ds_read_b128 v[16:19], v43 offset:24576
	s_waitcnt lgkmcnt(0)
	v_mfma_f32_16x16x32_bf16 v[16:19], v[16:19], v[4:7], 0
	v_mfma_f32_16x16x32_bf16 v[16:19], v[20:23], v[12:15], v[16:19]
	ds_read_b128 v[20:23], v100 offset:24576
	s_waitcnt lgkmcnt(0)
	v_mfma_f32_16x16x32_bf16 v[16:19], v[20:23], v[0:3], v[16:19]
	ds_read_b128 v[20:23], v83 offset:24576
	s_waitcnt lgkmcnt(0)
	v_mfma_f32_16x16x32_bf16 v[16:19], v[20:23], v[8:11], v[16:19]
	ds_read_b128 v[20:23], v63 offset:28672
	s_nop 6
	v_pk_fma_f32 v[92:93], v[40:41], v[18:19], v[30:31] op_sel_hi:[0,1,1]
	v_pk_fma_f32 v[94:95], v[40:41], v[16:17], v[28:29] op_sel_hi:[0,1,1]
	ds_read_b128 v[16:19], v43 offset:28672
	s_waitcnt lgkmcnt(0)
	v_mfma_f32_16x16x32_bf16 v[16:19], v[16:19], v[4:7], 0
	v_mfma_f32_16x16x32_bf16 v[16:19], v[20:23], v[12:15], v[16:19]
	ds_read_b128 v[20:23], v100 offset:28672
	s_waitcnt lgkmcnt(0)
	v_mfma_f32_16x16x32_bf16 v[16:19], v[20:23], v[0:3], v[16:19]
	ds_read_b128 v[20:23], v83 offset:28672
	s_waitcnt lgkmcnt(0)
	v_mfma_f32_16x16x32_bf16 v[16:19], v[20:23], v[8:11], v[16:19]
	ds_read_b128 v[20:23], v63 offset:32768
	s_nop 6
	v_pk_fma_f32 v[96:97], v[40:41], v[18:19], v[26:27] op_sel_hi:[0,1,1]
	v_pk_fma_f32 v[98:99], v[40:41], v[16:17], v[24:25] op_sel_hi:[0,1,1]
	ds_read_b128 v[16:19], v43 offset:32768
	s_waitcnt lgkmcnt(0)
	v_mfma_f32_16x16x32_bf16 v[16:19], v[16:19], v[4:7], 0
	v_mfma_f32_16x16x32_bf16 v[16:19], v[20:23], v[12:15], v[16:19]
	ds_read_b128 v[20:23], v100 offset:32768
	s_waitcnt lgkmcnt(0)
	v_mfma_f32_16x16x32_bf16 v[16:19], v[20:23], v[0:3], v[16:19]
	ds_read_b128 v[20:23], v83 offset:32768
	s_waitcnt lgkmcnt(0)
	v_mfma_f32_16x16x32_bf16 v[16:19], v[20:23], v[8:11], v[16:19]
	ds_read_b128 v[20:23], v63 offset:36864
	s_nop 6
	v_pk_fma_f32 v[40:41], v[42:43], v[18:19], v[48:49] op_sel_hi:[0,1,1]
	v_pk_fma_f32 v[38:39], v[42:43], v[16:17], v[50:51] op_sel_hi:[0,1,1]
	ds_read_b128 v[16:19], v43 offset:36864
	s_waitcnt lgkmcnt(0)
	v_mfma_f32_16x16x32_bf16 v[16:19], v[16:19], v[4:7], 0
	ds_read_b128 v[48:51], v63 offset:57344
	v_mfma_f32_16x16x32_bf16 v[16:19], v[20:23], v[12:15], v[16:19]
	ds_read_b128 v[20:23], v100 offset:36864
	s_waitcnt lgkmcnt(0)
	v_mfma_f32_16x16x32_bf16 v[16:19], v[20:23], v[0:3], v[16:19]
	ds_read_b128 v[20:23], v83 offset:36864
	s_waitcnt lgkmcnt(0)
	v_mfma_f32_16x16x32_bf16 v[16:19], v[20:23], v[8:11], v[16:19]
	ds_read_b128 v[20:23], v63 offset:40960
	s_nop 6
	v_pk_fma_f32 v[36:37], v[42:43], v[18:19], v[44:45] op_sel_hi:[0,1,1]
	v_pk_fma_f32 v[34:35], v[42:43], v[16:17], v[46:47] op_sel_hi:[0,1,1]
	ds_read_b128 v[16:19], v43 offset:40960
	s_waitcnt lgkmcnt(0)
	v_mfma_f32_16x16x32_bf16 v[16:19], v[16:19], v[4:7], 0
	ds_read_b128 v[44:47], v63 offset:53248
	v_mfma_f32_16x16x32_bf16 v[16:19], v[20:23], v[12:15], v[16:19]
	ds_read_b128 v[20:23], v100 offset:40960
	s_waitcnt lgkmcnt(0)
	v_mfma_f32_16x16x32_bf16 v[16:19], v[20:23], v[0:3], v[16:19]
	ds_read_b128 v[20:23], v83 offset:40960
	s_waitcnt lgkmcnt(0)
	v_mfma_f32_16x16x32_bf16 v[16:19], v[20:23], v[8:11], v[16:19]
	ds_read_b128 v[20:23], v63 offset:45056
	s_nop 6
	v_pk_fma_f32 v[32:33], v[42:43], v[18:19], v[58:59] op_sel_hi:[0,1,1]
	v_pk_fma_f32 v[30:31], v[42:43], v[16:17], v[56:57] op_sel_hi:[0,1,1]
	ds_read_b128 v[16:19], v43 offset:45056
	s_waitcnt lgkmcnt(0)
	v_mfma_f32_16x16x32_bf16 v[16:19], v[16:19], v[4:7], 0
	v_lshlrev_b32_e32 v56, 16, v75
	v_and_b32_e32 v57, 0xffff0000, v75
	v_and_b32_e32 v75, 0xffff0000, v73
	v_mfma_f32_16x16x32_bf16 v[16:19], v[20:23], v[12:15], v[16:19]
	ds_read_b128 v[20:23], v100 offset:45056
	s_waitcnt lgkmcnt(0)
	v_mfma_f32_16x16x32_bf16 v[16:19], v[20:23], v[0:3], v[16:19]
	ds_read_b128 v[20:23], v83 offset:45056
	s_waitcnt lgkmcnt(0)
	v_mfma_f32_16x16x32_bf16 v[16:19], v[20:23], v[8:11], v[16:19]
	ds_read_b128 v[20:23], v63 offset:49152
	s_nop 6
	v_pk_fma_f32 v[28:29], v[42:43], v[18:19], v[54:55] op_sel_hi:[0,1,1]
	v_pk_fma_f32 v[26:27], v[42:43], v[16:17], v[52:53] op_sel_hi:[0,1,1]
	ds_read_b128 v[16:19], v43 offset:49152
	s_waitcnt lgkmcnt(0)
	v_mfma_f32_16x16x32_bf16 v[16:19], v[16:19], v[4:7], 0
	v_lshlrev_b32_e32 v52, 16, v77
	v_and_b32_e32 v53, 0xffff0000, v77
	v_mfma_f32_16x16x32_bf16 v[16:19], v[20:23], v[12:15], v[16:19]
	ds_read_b128 v[20:23], v100 offset:49152
	s_waitcnt lgkmcnt(0)
	v_mfma_f32_16x16x32_bf16 v[16:19], v[20:23], v[0:3], v[16:19]
	ds_read_b128 v[20:23], v83 offset:49152
	s_waitcnt lgkmcnt(0)
	v_mfma_f32_16x16x32_bf16 v[16:19], v[20:23], v[8:11], v[16:19]
	s_nop 7
	v_pk_fma_f32 v[24:25], v[42:43], v[18:19], v[84:85] op_sel_hi:[0,1,1]
	v_pk_fma_f32 v[22:23], v[42:43], v[16:17], v[86:87] op_sel_hi:[0,1,1]
	ds_read_b128 v[16:19], v43 offset:53248
	s_waitcnt lgkmcnt(0)
	v_mfma_f32_16x16x32_bf16 v[16:19], v[16:19], v[4:7], 0
	v_mfma_f32_16x16x32_bf16 v[16:19], v[44:47], v[12:15], v[16:19]
	ds_read_b128 v[44:47], v100 offset:53248
	s_waitcnt lgkmcnt(0)
	v_mfma_f32_16x16x32_bf16 v[16:19], v[44:47], v[0:3], v[16:19]
	ds_read_b128 v[44:47], v83 offset:53248
	s_waitcnt lgkmcnt(0)
; __device__ __forceinline__ float bf_lo(unsigned u) { return __uint_as_float(u << 16); }
; __device__ __forceinline__ float silu_f(float x) { return x * __builtin_amdgcn_rcpf(1.0f + __expf(-x)); }
; __device__ __forceinline__ void ret_out(const bf16_t* proj, const float* cosT, const float* sinT, const float* decay, const float* gn_g, const float* gn_b,
;                         const bf16_t* states, bf16_t* mix, unsigned char* lds, int tid, int bx) {
;     ...
;         float sm = 0.f;
; #pragma unroll
;         for (int e8 = 0; e8 < 8; ++e8) sm += (acc[e8][0] + acc[e8][1]) + (acc[e8][2] + acc[e8][3]);
;         sm += __shfl_xor(sm, 16); sm += __shfl_xor(sm, 32);
;         const float mu = sm * (1.0f / 128.0f);
;         float vs = 0.f;
; #pragma unroll
;         for (int e8 = 0; e8 < 8; ++e8)
; #pragma unroll
;             for (int r = 0; r < 4; ++r) { const float dlt = acc[e8][r] - mu; vs += dlt * dlt; }
;         vs += __shfl_xor(vs, 16); vs += __shfl_xor(vs, 32);
;         const float rstd = 1.0f / sqrtf(vs * (1.0f / 128.0f) + 1e-5f);
;         bf16_t* op = mix + (size_t)(b * SEQ + tq) * 1024 + h * 128 + 4 * fq;
; #pragma unroll
;         for (int e8 = 0; e8 < 8; ++e8) {
;             const u32x2 gw = gwv[e8];
;             const float4 gg = *(const float4*)(gnl + h * 128 + 16 * e8 + 4 * fq), gb = *(const float4*)(gnl + 768 + h * 128 + 16 * e8 + 4 * fq);
;             const float y0 = ((acc[e8][0] - mu) * rstd * gg.x + gb.x) * silu_f(bf_lo(gw.x));
	v_mfma_f32_16x16x32_bf16 v[16:19], v[44:47], v[8:11], v[16:19]
	ds_read_b128 v[44:47], v43 offset:57344
	s_nop 6
	v_pk_fma_f32 v[20:21], v[42:43], v[18:19], v[88:89] op_sel_hi:[0,1,1]
	s_waitcnt lgkmcnt(0)
	v_mfma_f32_16x16x32_bf16 v[44:47], v[44:47], v[4:7], 0
	v_fma_f32 v18, v42, v16, v90
	v_fma_f32 v19, v42, v17, v91
	v_mfma_f32_16x16x32_bf16 v[44:47], v[48:51], v[12:15], v[44:47]
	ds_read_b128 v[48:51], v100 offset:57344
	s_waitcnt lgkmcnt(0)
	v_mfma_f32_16x16x32_bf16 v[44:47], v[48:51], v[0:3], v[44:47]
	ds_read_b128 v[48:51], v83 offset:57344
	s_waitcnt lgkmcnt(0)
	v_mfma_f32_16x16x32_bf16 v[44:47], v[48:51], v[8:11], v[44:47]
	s_nop 7
	v_pk_fma_f32 v[48:49], v[42:43], v[46:47], v[92:93] op_sel_hi:[0,1,1]
	v_pk_fma_f32 v[16:17], v[42:43], v[44:45], v[94:95] op_sel_hi:[0,1,1]
	ds_read_b128 v[44:47], v43 offset:61440
	s_waitcnt lgkmcnt(0)
	v_mfma_f32_16x16x32_bf16 v[4:7], v[44:47], v[4:7], 0
	ds_read_b128 v[44:47], v63 offset:61440
	s_waitcnt lgkmcnt(0)
	v_mfma_f32_16x16x32_bf16 v[4:7], v[44:47], v[12:15], v[4:7]
	ds_read_b128 v[12:15], v100 offset:61440
	s_waitcnt lgkmcnt(0)
	v_mfma_f32_16x16x32_bf16 v[0:3], v[12:15], v[0:3], v[4:7]
	s_nop 4
	ds_read_b128 v[4:7], v83 offset:61440
	s_waitcnt lgkmcnt(0)
	v_mfma_f32_16x16x32_bf16 v[0:3], v[4:7], v[8:11], v[0:3]
	v_mov_b32_e32 v4, v38
	v_mov_b32_e32 v5, v34
	v_mov_b32_e32 v6, v39
	v_mov_b32_e32 v7, v35
	v_pk_add_f32 v[4:5], v[4:5], v[6:7]
	v_mov_b32_e32 v6, v40
	v_mov_b32_e32 v7, v36
	v_mov_b32_e32 v8, v41
	v_mov_b32_e32 v9, v37
	v_pk_add_f32 v[6:7], v[6:7], v[8:9]
	v_mov_b32_e32 v8, v30
	v_pk_add_f32 v[4:5], v[4:5], v[6:7]
	v_pk_mov_b32 v[6:7], v[30:31], v[32:33] op_sel:[1,0]
	v_mov_b32_e32 v9, v33
	v_pk_add_f32 v[6:7], v[6:7], v[8:9]
	v_add_f32_e32 v4, 0, v4
	v_pk_add_f32 v[6:7], v[6:7], v[6:7] op_sel:[0,1] op_sel_hi:[1,0]
	v_add_f32_e32 v4, v4, v5
	v_add_f32_e32 v8, v26, v27
	v_add_f32_e32 v10, v28, v29
	v_mov_b32_e32 v5, v22
	v_mov_b32_e32 v7, v23
	v_mov_b32_e32 v9, v24
	v_mov_b32_e32 v11, v25
	v_pk_add_f32 v[4:5], v[4:5], v[6:7]
	v_pk_add_f32 v[6:7], v[8:9], v[10:11]
	v_mov_b32_e32 v8, v18
	v_pk_add_f32 v[4:5], v[4:5], v[6:7]
	v_pk_mov_b32 v[6:7], v[18:19], v[20:21] op_sel:[1,0]
	v_mov_b32_e32 v9, v21
	v_pk_add_f32 v[6:7], v[6:7], v[8:9]
	v_pk_fma_f32 v[2:3], v[42:43], v[2:3], v[96:97] op_sel_hi:[0,1,1]
	v_pk_fma_f32 v[0:1], v[42:43], v[0:1], v[98:99] op_sel_hi:[0,1,1]
	v_pk_add_f32 v[4:5], v[4:5], v[4:5] op_sel:[0,1] op_sel_hi:[1,0]
	v_pk_add_f32 v[6:7], v[6:7], v[6:7] op_sel:[0,1] op_sel_hi:[1,0]
	v_add_f32_e32 v8, v16, v17
	v_add_f32_e32 v10, v48, v49
	v_mov_b32_e32 v5, v0
	v_mov_b32_e32 v7, v1
	v_mov_b32_e32 v9, v2
	v_mov_b32_e32 v11, v3
	v_pk_add_f32 v[4:5], v[4:5], v[6:7]
	v_pk_add_f32 v[6:7], v[8:9], v[10:11]
	s_nop 0
	v_pk_add_f32 v[4:5], v[4:5], v[6:7]
	s_nop 0
	v_add_f32_e32 v4, v4, v5
	ds_bpermute_b32 v5, v61, v4
	s_waitcnt lgkmcnt(0)
	v_add_f32_e32 v4, v4, v5
	ds_bpermute_b32 v5, v82, v4
	s_waitcnt lgkmcnt(0)
	v_add_f32_e32 v4, v4, v5
	v_mul_f32_e32 v14, 0x3c000000, v4
	v_pk_add_f32 v[6:7], v[48:49], v[14:15] op_sel_hi:[1,0] neg_lo:[0,1] neg_hi:[0,1]
	v_pk_add_f32 v[4:5], v[0:1], v[14:15] op_sel_hi:[1,0] neg_lo:[0,1] neg_hi:[0,1]
	v_pk_add_f32 v[2:3], v[2:3], v[14:15] op_sel_hi:[1,0] neg_lo:[0,1] neg_hi:[0,1]
	v_add_u32_e32 v15, s0, v62
	v_lshlrev_b32_e32 v48, 16, v79
	v_add_u32_e32 v83, 0x21000, v15
	v_add_u32_e32 v148, 0x21c00, v15
	v_pk_add_f32 v[62:63], v[40:41], v[14:15] op_sel_hi:[1,0] neg_lo:[0,1] neg_hi:[0,1]
	v_mul_f32_e32 v15, 0xbfb8aa3b, v48
	v_exp_f32_e32 v15, v15
	v_and_b32_e32 v49, 0xffff0000, v79
	v_lshlrev_b64 v[0:1], 11, v[80:81]
	v_pk_mul_f32 v[80:81], v[62:63], v[62:63]
	v_add_f32_e32 v15, 1.0, v15
	v_rcp_f32_e32 v50, v15
	v_mul_f32_e32 v15, 0xbfb8aa3b, v49
	v_exp_f32_e32 v15, v15
	v_pk_mul_f32 v[8:9], v[6:7], v[6:7]
	v_pk_mul_f32 v[10:11], v[4:5], v[4:5]
	v_pk_mul_f32 v[12:13], v[2:3], v[2:3]
	v_add_f32_e32 v15, 1.0, v15
	v_pk_add_f32 v[86:87], v[38:39], v[14:15] op_sel_hi:[1,0] neg_lo:[0,1] neg_hi:[0,1]
	v_lshlrev_b32_e32 v38, 16, v78
	v_rcp_f32_e32 v51, v15
	v_mul_f32_e32 v15, 0xbfb8aa3b, v38
	v_exp_f32_e32 v15, v15
	v_and_b32_e32 v39, 0xffff0000, v78
	v_pk_mul_f32 v[84:85], v[50:51], v[48:49]
	v_pk_mul_f32 v[88:89], v[86:87], v[86:87]
	v_add_f32_e32 v15, 1.0, v15
	v_rcp_f32_e32 v48, v15
	v_mul_f32_e32 v15, 0xbfb8aa3b, v39
	v_exp_f32_e32 v15, v15
	v_add_f32_e32 v88, v88, v89
	v_add_f32_e32 v80, v80, v88
	v_add_f32_e32 v80, v81, v80
	v_add_f32_e32 v15, 1.0, v15
	v_rcp_f32_e32 v49, v15
	v_pk_add_f32 v[92:93], v[36:37], v[14:15] op_sel_hi:[1,0] neg_lo:[0,1] neg_hi:[0,1]
	v_mul_f32_e32 v15, 0xbfb8aa3b, v52
	v_exp_f32_e32 v15, v15
	v_pk_mul_f32 v[94:95], v[92:93], v[92:93]
	ds_read_b128 v[40:43], v83
	ds_read_b128 v[44:47], v148
	v_pk_mul_f32 v[90:91], v[48:49], v[38:39]
	v_add_f32_e32 v15, 1.0, v15
	v_rcp_f32_e32 v54, v15
	v_mul_f32_e32 v15, 0xbfb8aa3b, v53
	v_exp_f32_e32 v15, v15
	ds_read_b128 v[36:39], v83 offset:64
	ds_read_b128 v[48:51], v148 offset:64
	v_lshl_add_u64 v[0:1], s[42:43], 0, v[0:1]
	v_lshl_add_u64 v[0:1], v[0:1], 0, s[46:47]
	v_add_f32_e32 v15, 1.0, v15
	v_pk_add_f32 v[98:99], v[34:35], v[14:15] op_sel_hi:[1,0] neg_lo:[0,1] neg_hi:[0,1]
	v_lshlrev_b32_e32 v34, 16, v76
	v_rcp_f32_e32 v55, v15
	v_mul_f32_e32 v15, 0xbfb8aa3b, v34
	v_exp_f32_e32 v15, v15
	v_and_b32_e32 v35, 0xffff0000, v76
	v_pk_mul_f32 v[96:97], v[54:55], v[52:53]
	v_pk_mul_f32 v[100:101], v[98:99], v[98:99]
	v_add_f32_e32 v15, 1.0, v15
	v_rcp_f32_e32 v52, v15
	v_mul_f32_e32 v15, 0xbfb8aa3b, v35
	v_exp_f32_e32 v15, v15
	v_add_f32_e32 v80, v100, v80
	v_add_f32_e32 v80, v101, v80
	v_add_f32_e32 v80, v94, v80
	v_add_f32_e32 v15, 1.0, v15
	v_rcp_f32_e32 v53, v15
; __device__ __forceinline__ float bf_lo(unsigned u) { return __uint_as_float(u << 16); }
; __device__ __forceinline__ float bf_hi(unsigned u) { return __uint_as_float(u & 0xffff0000u); }
; __device__ __forceinline__ float silu_f(float x) { return x * __builtin_amdgcn_rcpf(1.0f + __expf(-x)); }
; __device__ __forceinline__ void ret_out(const bf16_t* proj, const float* cosT, const float* sinT, const float* decay, const float* gn_g, const float* gn_b,
;                         const bf16_t* states, bf16_t* mix, unsigned char* lds, int tid, int bx) {
;     ...
;         float vs = 0.f;
; #pragma unroll
;         for (int e8 = 0; e8 < 8; ++e8)
; #pragma unroll
;             for (int r = 0; r < 4; ++r) { const float dlt = acc[e8][r] - mu; vs += dlt * dlt; }
;         vs += __shfl_xor(vs, 16); vs += __shfl_xor(vs, 32);
;         const float rstd = 1.0f / sqrtf(vs * (1.0f / 128.0f) + 1e-5f);
;         bf16_t* op = mix + (size_t)(b * SEQ + tq) * 1024 + h * 128 + 4 * fq;
; #pragma unroll
;         for (int e8 = 0; e8 < 8; ++e8) {
;             const u32x2 gw = gwv[e8];
;             const float4 gg = *(const float4*)(gnl + h * 128 + 16 * e8 + 4 * fq), gb = *(const float4*)(gnl + 768 + h * 128 + 16 * e8 + 4 * fq);
;             const float y0 = ((acc[e8][0] - mu) * rstd * gg.x + gb.x) * silu_f(bf_lo(gw.x));
;             const float y1 = ((acc[e8][1] - mu) * rstd * gg.y + gb.y) * silu_f(bf_hi(gw.x));
;             const float y2 = ((acc[e8][2] - mu) * rstd * gg.z + gb.z) * silu_f(bf_lo(gw.y));
;             const float y3 = ((acc[e8][3] - mu) * rstd * gg.w + gb.w) * silu_f(bf_hi(gw.y));
	v_pk_add_f32 v[104:105], v[32:33], v[14:15] op_sel_hi:[1,0] neg_lo:[0,1] neg_hi:[0,1]
	v_mul_f32_e32 v15, 0xbfb8aa3b, v56
	v_exp_f32_e32 v15, v15
	v_add_f32_e32 v80, v95, v80
	v_pk_mul_f32 v[106:107], v[104:105], v[104:105]
	v_lshl_add_u64 v[0:1], v[0:1], 0, v[154:155]
	v_add_f32_e32 v15, 1.0, v15
	v_rcp_f32_e32 v58, v15
	v_mul_f32_e32 v15, 0xbfb8aa3b, v57
	v_exp_f32_e32 v15, v15
	v_pk_mul_f32 v[102:103], v[52:53], v[34:35]
	ds_read_b128 v[32:35], v83 offset:128
	ds_read_b128 v[52:55], v148 offset:128
	v_add_f32_e32 v15, 1.0, v15
	v_pk_add_f32 v[110:111], v[30:31], v[14:15] op_sel_hi:[1,0] neg_lo:[0,1] neg_hi:[0,1]
	v_lshlrev_b32_e32 v30, 16, v74
	v_rcp_f32_e32 v59, v15
	v_mul_f32_e32 v15, 0xbfb8aa3b, v30
	v_exp_f32_e32 v15, v15
	v_and_b32_e32 v31, 0xffff0000, v74
	v_pk_mul_f32 v[108:109], v[58:59], v[56:57]
	v_lshlrev_b32_e32 v74, 16, v73
	v_add_f32_e32 v15, 1.0, v15
	v_rcp_f32_e32 v56, v15
	v_mul_f32_e32 v15, 0xbfb8aa3b, v31
	v_exp_f32_e32 v15, v15
	v_pk_mul_f32 v[112:113], v[110:111], v[110:111]
	v_add_f32_e32 v15, 1.0, v15
	v_rcp_f32_e32 v57, v15
	v_pk_add_f32 v[116:117], v[28:29], v[14:15] op_sel_hi:[1,0] neg_lo:[0,1] neg_hi:[0,1]
	v_mul_f32_e32 v15, 0xbfb8aa3b, v74
	v_exp_f32_e32 v15, v15
	v_add_f32_e32 v80, v112, v80
	v_add_f32_e32 v80, v113, v80
	v_add_f32_e32 v80, v106, v80
	v_add_f32_e32 v15, 1.0, v15
	v_rcp_f32_e32 v76, v15
	v_mul_f32_e32 v15, 0xbfb8aa3b, v75
	v_exp_f32_e32 v15, v15
	v_add_f32_e32 v80, v107, v80
	v_pk_mul_f32 v[118:119], v[116:117], v[116:117]
	v_pk_mul_f32 v[114:115], v[56:57], v[30:31]
	v_add_f32_e32 v15, 1.0, v15
	v_pk_add_f32 v[122:123], v[26:27], v[14:15] op_sel_hi:[1,0] neg_lo:[0,1] neg_hi:[0,1]
	v_lshlrev_b32_e32 v26, 16, v72
	v_rcp_f32_e32 v77, v15
	v_mul_f32_e32 v15, 0xbfb8aa3b, v26
	v_exp_f32_e32 v15, v15
	v_and_b32_e32 v27, 0xffff0000, v72
	v_pk_mul_f32 v[120:121], v[76:77], v[74:75]
	v_lshlrev_b32_e32 v76, 16, v71
	v_add_f32_e32 v15, 1.0, v15
	v_rcp_f32_e32 v72, v15
	v_mul_f32_e32 v15, 0xbfb8aa3b, v27
	v_exp_f32_e32 v15, v15
	v_and_b32_e32 v77, 0xffff0000, v71
	v_pk_mul_f32 v[124:125], v[122:123], v[122:123]
	ds_read_b128 v[28:31], v83 offset:192
	ds_read_b128 v[56:59], v148 offset:192
	v_add_f32_e32 v15, 1.0, v15
	v_rcp_f32_e32 v73, v15
	v_pk_add_f32 v[128:129], v[24:25], v[14:15] op_sel_hi:[1,0] neg_lo:[0,1] neg_hi:[0,1]
	v_mul_f32_e32 v15, 0xbfb8aa3b, v76
	v_exp_f32_e32 v15, v15
	v_add_f32_e32 v80, v124, v80
	v_add_f32_e32 v80, v125, v80
	v_add_f32_e32 v80, v118, v80
	v_add_f32_e32 v15, 1.0, v15
	v_rcp_f32_e32 v78, v15
	v_mul_f32_e32 v15, 0xbfb8aa3b, v77
	v_exp_f32_e32 v15, v15
	v_add_f32_e32 v80, v119, v80
	v_pk_mul_f32 v[130:131], v[128:129], v[128:129]
	v_pk_mul_f32 v[126:127], v[72:73], v[26:27]
	v_add_f32_e32 v15, 1.0, v15
	v_pk_add_f32 v[134:135], v[22:23], v[14:15] op_sel_hi:[1,0] neg_lo:[0,1] neg_hi:[0,1]
	v_lshlrev_b32_e32 v22, 16, v70
	v_rcp_f32_e32 v79, v15
	v_mul_f32_e32 v15, 0xbfb8aa3b, v22
	v_exp_f32_e32 v15, v15
	v_and_b32_e32 v23, 0xffff0000, v70
	v_pk_mul_f32 v[136:137], v[134:135], v[134:135]
	ds_read_b128 v[24:27], v83 offset:256
	ds_read_b128 v[72:75], v148 offset:256
	v_add_f32_e32 v15, 1.0, v15
	v_rcp_f32_e32 v70, v15
	v_mul_f32_e32 v15, 0xbfb8aa3b, v23
	v_exp_f32_e32 v15, v15
	v_add_f32_e32 v80, v136, v80
	v_add_f32_e32 v80, v137, v80
	v_add_f32_e32 v80, v130, v80
	v_add_f32_e32 v15, 1.0, v15
	v_rcp_f32_e32 v71, v15
	v_pk_add_f32 v[138:139], v[20:21], v[14:15] op_sel_hi:[1,0] neg_lo:[0,1] neg_hi:[0,1]
	v_mul_f32_e32 v15, 0xbfb8aa3b, v142
	v_exp_f32_e32 v15, v15
	v_add_f32_e32 v80, v131, v80
	v_pk_mul_f32 v[140:141], v[138:139], v[138:139]
	v_pk_mul_f32 v[132:133], v[78:79], v[76:77]
	v_add_f32_e32 v15, 1.0, v15
	v_rcp_f32_e32 v144, v15
	v_mul_f32_e32 v15, 0xbfb8aa3b, v143
	v_exp_f32_e32 v15, v15
	v_pk_mul_f32 v[70:71], v[70:71], v[22:23]
	ds_read_b128 v[20:23], v83 offset:320
	ds_read_b128 v[76:79], v148 offset:320
	v_add_f32_e32 v15, 1.0, v15
	v_rcp_f32_e32 v145, v15
	v_pk_add_f32 v[18:19], v[18:19], v[14:15] op_sel_hi:[1,0] neg_lo:[0,1] neg_hi:[0,1]
	v_mul_f32_e32 v15, 0xbfb8aa3b, v146
	v_exp_f32_e32 v15, v15
	v_pk_mul_f32 v[142:143], v[144:145], v[142:143]
	v_pk_mul_f32 v[144:145], v[18:19], v[18:19]
	v_add_f32_e32 v15, 1.0, v15
	v_rcp_f32_e32 v68, v15
	v_mul_f32_e32 v15, 0xbfb8aa3b, v147
	v_exp_f32_e32 v15, v15
	v_add_f32_e32 v80, v144, v80
	v_add_f32_e32 v80, v145, v80
	v_add_f32_e32 v80, v140, v80
	v_add_f32_e32 v15, 1.0, v15
	v_pk_add_f32 v[16:17], v[16:17], v[14:15] op_sel_hi:[1,0] neg_lo:[0,1] neg_hi:[0,1]
	v_rcp_f32_e32 v69, v15
	v_pk_mul_f32 v[14:15], v[16:17], v[16:17]
	v_add_f32_e32 v80, v141, v80
	v_add_f32_e32 v14, v14, v80
	v_add_f32_e32 v14, v15, v14
	v_add_f32_e32 v8, v8, v14
	v_add_f32_e32 v8, v9, v8
	v_add_f32_e32 v8, v10, v8
	v_add_f32_e32 v8, v11, v8
	v_add_f32_e32 v8, v12, v8
	v_add_f32_e32 v8, v13, v8
	ds_bpermute_b32 v9, v61, v8
	v_pk_mul_f32 v[68:69], v[68:69], v[146:147]
	s_waitcnt lgkmcnt(0)
	v_add_f32_e32 v8, v8, v9
	ds_bpermute_b32 v9, v82, v8
	s_waitcnt lgkmcnt(0)
; __device__ __forceinline__ float bf_lo(unsigned u) { return __uint_as_float(u << 16); }
; __device__ __forceinline__ float bf_hi(unsigned u) { return __uint_as_float(u & 0xffff0000u); }
; __device__ __forceinline__ float silu_f(float x) { return x * __builtin_amdgcn_rcpf(1.0f + __expf(-x)); }
; __device__ __forceinline__ void ret_out(const bf16_t* proj, const float* cosT, const float* sinT, const float* decay, const float* gn_g, const float* gn_b,
;                         const bf16_t* states, bf16_t* mix, unsigned char* lds, int tid, int bx) {
;     ...
;         const float rstd = 1.0f / sqrtf(vs * (1.0f / 128.0f) + 1e-5f);
;         bf16_t* op = mix + (size_t)(b * SEQ + tq) * 1024 + h * 128 + 4 * fq;
; #pragma unroll
;         for (int e8 = 0; e8 < 8; ++e8) {
;             const u32x2 gw = gwv[e8];
;             const float4 gg = *(const float4*)(gnl + h * 128 + 16 * e8 + 4 * fq), gb = *(const float4*)(gnl + 768 + h * 128 + 16 * e8 + 4 * fq);
;             const float y0 = ((acc[e8][0] - mu) * rstd * gg.x + gb.x) * silu_f(bf_lo(gw.x));
;             const float y1 = ((acc[e8][1] - mu) * rstd * gg.y + gb.y) * silu_f(bf_hi(gw.x));
;             const float y2 = ((acc[e8][2] - mu) * rstd * gg.z + gb.z) * silu_f(bf_lo(gw.y));
;             const float y3 = ((acc[e8][3] - mu) * rstd * gg.w + gb.w) * silu_f(bf_hi(gw.y));
;             u32x2 w; w.x = cvt_pk_bf16(y0, y1); w.y = cvt_pk_bf16(y2, y3);
;             *(u32x2*)(op + 16 * e8) = w;
;         }
	v_add_f32_e32 v8, v8, v9
	v_fmamk_f32 v8, v8, 0x3c000000, v175
	v_cmp_gt_f32_e32 vcc, s64, v8
	v_mul_f32_e32 v9, 0x4f800000, v8
	s_nop 0
	v_cndmask_b32_e32 v8, v8, v9, vcc
	v_sqrt_f32_e32 v9, v8
	s_nop 0
	v_add_u32_e32 v10, -1, v9
	v_fma_f32 v11, -v10, v9, v8
	v_cmp_ge_f32_e64 s[36:37], 0, v11
	v_add_u32_e32 v11, 1, v9
	s_nop 0
	v_cndmask_b32_e64 v10, v9, v10, s[36:37]
	v_fma_f32 v9, -v11, v9, v8
	v_cmp_lt_f32_e64 s[36:37], 0, v9
	s_nop 1
	v_cndmask_b32_e64 v9, v10, v11, s[36:37]
	v_mul_f32_e32 v10, 0x37800000, v9
	v_cndmask_b32_e32 v9, v9, v10, vcc
	v_cmp_class_f32_e32 vcc, v8, v176
	s_nop 1
	v_cndmask_b32_e32 v8, v9, v8, vcc
	v_div_scale_f32 v9, s[0:1], v8, v8, 1.0
	v_rcp_f32_e32 v10, v9
	s_nop 0
	v_fma_f32 v11, -v9, v10, 1.0
	v_fmac_f32_e32 v10, v11, v10
	v_div_scale_f32 v11, vcc, 1.0, v8, 1.0
	v_mul_f32_e32 v12, v11, v10
	v_fma_f32 v13, -v9, v12, v11
	v_fmac_f32_e32 v12, v13, v10
	v_fma_f32 v9, -v9, v12, v11
	v_div_fmas_f32 v9, v9, v10, v12
	v_div_fixup_f32 v80, v9, v8, 1.0
	v_bfe_u32 v88, v172, 4, 1
	v_mul_u32_u24_e32 v88, 24, v88
	s_nop 0
	v_add_co_u32_e32 v0, vcc, v0, v88
	s_nop 1
	v_addc_co_u32_e32 v1, vcc, 0, v1, vcc
	v_pk_mul_f32 v[8:9], v[86:87], v[80:81] op_sel_hi:[1,0]
	v_pk_mul_f32 v[10:11], v[62:63], v[80:81] op_sel_hi:[1,0]
	v_pk_fma_f32 v[8:9], v[40:41], v[8:9], v[44:45]
	v_pk_fma_f32 v[10:11], v[42:43], v[10:11], v[46:47]
	v_pk_mul_f32 v[8:9], v[90:91], v[8:9]
	v_pk_mul_f32 v[10:11], v[84:85], v[10:11]
	v_cvt_pk_bf16_f32 v8, v8, v9
	v_cvt_pk_bf16_f32 v9, v10, v11
	v_pk_mul_f32 v[40:41], v[98:99], v[80:81] op_sel_hi:[1,0]
	v_pk_mul_f32 v[42:43], v[92:93], v[80:81] op_sel_hi:[1,0]
	v_pk_fma_f32 v[40:41], v[36:37], v[40:41], v[48:49]
	v_pk_fma_f32 v[42:43], v[38:39], v[42:43], v[50:51]
	v_pk_mul_f32 v[40:41], v[102:103], v[40:41]
	v_pk_mul_f32 v[42:43], v[96:97], v[42:43]
	v_cvt_pk_bf16_f32 v10, v40, v41
	v_cvt_pk_bf16_f32 v11, v42, v43
	s_nop 1
	v_permlane16_swap_b32 v8, v10
	v_permlane16_swap_b32 v9, v11
	global_store_dwordx4 v[0:1], v[8:11], off
	s_nop 1
	v_pk_mul_f32 v[8:9], v[110:111], v[80:81] op_sel_hi:[1,0]
	v_pk_mul_f32 v[10:11], v[104:105], v[80:81] op_sel_hi:[1,0]
	v_pk_fma_f32 v[8:9], v[32:33], v[8:9], v[52:53]
	v_pk_fma_f32 v[10:11], v[34:35], v[10:11], v[54:55]
	v_pk_mul_f32 v[8:9], v[114:115], v[8:9]
	v_pk_mul_f32 v[10:11], v[108:109], v[10:11]
	v_cvt_pk_bf16_f32 v8, v8, v9
	v_cvt_pk_bf16_f32 v9, v10, v11
	v_pk_mul_f32 v[40:41], v[122:123], v[80:81] op_sel_hi:[1,0]
	v_pk_mul_f32 v[42:43], v[116:117], v[80:81] op_sel_hi:[1,0]
	v_pk_fma_f32 v[40:41], v[28:29], v[40:41], v[56:57]
	v_pk_fma_f32 v[42:43], v[30:31], v[42:43], v[58:59]
	v_pk_mul_f32 v[40:41], v[126:127], v[40:41]
	v_pk_mul_f32 v[42:43], v[120:121], v[42:43]
	v_cvt_pk_bf16_f32 v10, v40, v41
	v_cvt_pk_bf16_f32 v11, v42, v43
	s_nop 1
	v_permlane16_swap_b32 v8, v10
	v_permlane16_swap_b32 v9, v11
	global_store_dwordx4 v[0:1], v[8:11], off offset:64
	s_nop 1
	v_pk_mul_f32 v[8:9], v[134:135], v[80:81] op_sel_hi:[1,0]
	v_pk_mul_f32 v[10:11], v[128:129], v[80:81] op_sel_hi:[1,0]
	v_pk_fma_f32 v[8:9], v[24:25], v[8:9], v[72:73]
	v_pk_fma_f32 v[10:11], v[26:27], v[10:11], v[74:75]
	v_pk_mul_f32 v[8:9], v[70:71], v[8:9]
	v_pk_mul_f32 v[10:11], v[132:133], v[10:11]
	v_cvt_pk_bf16_f32 v8, v8, v9
	v_cvt_pk_bf16_f32 v9, v10, v11
	v_pk_mul_f32 v[40:41], v[18:19], v[80:81] op_sel_hi:[1,0]
	v_pk_mul_f32 v[42:43], v[138:139], v[80:81] op_sel_hi:[1,0]
	v_pk_fma_f32 v[40:41], v[20:21], v[40:41], v[76:77]
	v_pk_fma_f32 v[42:43], v[42:43], v[22:23], v[78:79]
	v_pk_mul_f32 v[40:41], v[68:69], v[40:41]
	v_pk_mul_f32 v[42:43], v[142:143], v[42:43]
	v_cvt_pk_bf16_f32 v10, v40, v41
	v_cvt_pk_bf16_f32 v11, v42, v43
	s_nop 1
	v_permlane16_swap_b32 v8, v10
	v_permlane16_swap_b32 v9, v11
	global_store_dwordx4 v[0:1], v[8:11], off offset:128
	s_nop 1
	ds_read_b128 v[8:11], v83 offset:384
	ds_read_b128 v[12:15], v148 offset:384
	s_waitcnt vmcnt(4)
	v_lshlrev_b32_e32 v18, 16, v66
	v_and_b32_e32 v19, 0xffff0000, v66
	v_pk_mul_f32 v[16:17], v[16:17], v[80:81] op_sel_hi:[1,0]
	v_mul_f32_e32 v20, 0xbfb8aa3b, v18
	s_waitcnt lgkmcnt(0)
	v_pk_fma_f32 v[8:9], v[16:17], v[8:9], v[12:13]
	v_mul_f32_e32 v12, 0xbfb8aa3b, v19
	v_exp_f32_e32 v20, v20
	v_exp_f32_e32 v12, v12
	v_pk_mul_f32 v[6:7], v[6:7], v[80:81] op_sel_hi:[1,0]
	v_pk_mul_f32 v[4:5], v[4:5], v[80:81] op_sel_hi:[1,0]
	v_add_f32_e32 v20, 1.0, v20
	v_add_f32_e32 v12, 1.0, v12
	v_rcp_f32_e32 v20, v20
	v_rcp_f32_e32 v21, v12
	v_pk_fma_f32 v[6:7], v[6:7], v[10:11], v[14:15]
	s_waitcnt vmcnt(3)
	v_lshlrev_b32_e32 v14, 16, v64
	v_and_b32_e32 v15, 0xffff0000, v64
	v_pk_mul_f32 v[12:13], v[20:21], v[18:19]
	v_pk_mul_f32 v[2:3], v[2:3], v[80:81] op_sel_hi:[1,0]
	v_pk_mul_f32 v[8:9], v[12:13], v[8:9]
	v_lshlrev_b32_e32 v12, 16, v67
	v_cvt_pk_bf16_f32 v8, v8, v9
	v_mul_f32_e32 v9, 0xbfb8aa3b, v12
	v_exp_f32_e32 v9, v9
	v_and_b32_e32 v13, 0xffff0000, v67
	v_add_f32_e32 v9, 1.0, v9
	v_rcp_f32_e32 v16, v9
	v_mul_f32_e32 v9, 0xbfb8aa3b, v13
	v_exp_f32_e32 v9, v9
	s_nop 0
	v_add_f32_e32 v9, 1.0, v9
	v_rcp_f32_e32 v17, v9
	s_nop 0
	v_pk_mul_f32 v[10:11], v[16:17], v[12:13]
	s_nop 0
	v_pk_mul_f32 v[6:7], v[10:11], v[6:7]
	v_mul_f32_e32 v16, 0xbfb8aa3b, v14
	v_cvt_pk_bf16_f32 v9, v6, v7
	v_mov_b32_e32 v84, v8
	v_mov_b32_e32 v85, v9
	ds_read_b128 v[6:9], v83 offset:448
	ds_read_b128 v[10:13], v148 offset:448
	v_exp_f32_e32 v16, v16
	s_waitcnt lgkmcnt(0)
	v_pk_fma_f32 v[4:5], v[4:5], v[6:7], v[10:11]
	v_mul_f32_e32 v6, 0xbfb8aa3b, v15
	v_exp_f32_e32 v6, v6
	v_add_f32_e32 v16, 1.0, v16
	v_rcp_f32_e32 v16, v16
	v_pk_fma_f32 v[2:3], v[2:3], v[8:9], v[12:13]
	v_add_f32_e32 v6, 1.0, v6
	v_rcp_f32_e32 v17, v6
	s_nop 0
	v_pk_mul_f32 v[6:7], v[16:17], v[14:15]
	s_nop 0
	v_pk_mul_f32 v[4:5], v[6:7], v[4:5]
	v_lshlrev_b32_e32 v6, 16, v65
	v_cvt_pk_bf16_f32 v86, v4, v5
	v_mul_f32_e32 v5, 0xbfb8aa3b, v6
	v_exp_f32_e32 v5, v5
	v_and_b32_e32 v7, 0xffff0000, v65
	v_add_f32_e32 v5, 1.0, v5
	v_rcp_f32_e32 v10, v5
	v_mul_f32_e32 v5, 0xbfb8aa3b, v7
	v_exp_f32_e32 v5, v5
	s_nop 0
	v_add_f32_e32 v5, 1.0, v5
	v_rcp_f32_e32 v11, v5
	s_nop 0
	v_pk_mul_f32 v[6:7], v[10:11], v[6:7]
	s_nop 0
	v_pk_mul_f32 v[2:3], v[6:7], v[2:3]
	s_nop 0
	v_cvt_pk_bf16_f32 v87, v2, v3
	s_nop 1
	v_permlane16_swap_b32 v84, v86
	v_permlane16_swap_b32 v85, v87
	global_store_dwordx4 v[0:1], v[84:87], off offset:192
	s_cbranch_scc1 .LBB0_189
